# scan compute: (beta,kappa) of two steps fetched by one ds_read_b128 two steps ahead (9.5 instead of 10 LDS reads per step)
# baseline (speedup 1.0000x reference)
.Lscan_chunk:
	s_and_b32 s1, s0, 1
	s_lshl_b32 s8, s1, 12
	s_mul_i32 s1, s1, 0xb100
	v_add_u32_e32 v30, s1, v197
	v_lshl_add_u32 v31, v195, 2, s1
	v_mov_b32_e32 v1, s1
	v_cndmask_b32_e64 v32, v34, v1, s[18:19]
	v_add_u32_e32 v1, s8, v207
	s_nop 0
	v_cndmask_b32_e64 v33, v35, v1, s[22:23]
	ds_read_b128 v[36:39], v30 offset:24576
	ds_read_b128 v[40:43], v30 offset:24592
	ds_read_b128 v[44:47], v30 offset:16384
	ds_read_b128 v[48:51], v30 offset:16400
	ds_read_b128 v[52:55], v30 offset:32768
	ds_read_b128 v[56:59], v30 offset:32784
	ds_read_b128 v[60:63], v30 offset:0
	ds_read_b128 v[64:67], v30 offset:16
	ds_read_b32 v15, v31 offset:40960
	ds_read_b128 v[142:145], v32 offset:45056
	ds_read_b128 v[68:71], v30 offset:24832
	ds_read_b128 v[72:75], v30 offset:24848
	ds_read_b128 v[76:79], v30 offset:16640
	ds_read_b128 v[80:83], v30 offset:16656
	ds_read_b128 v[84:87], v30 offset:33024
	ds_read_b128 v[88:91], v30 offset:33040
	ds_read_b128 v[134:137], v30 offset:256
	ds_read_b128 v[138:141], v30 offset:272
	ds_read_b32 v17, v31 offset:41088
	ds_read_b128 v[146:149], v32 offset:45072
	s_waitcnt lgkmcnt(10)
	v_pk_mul_f32 v[10:11], v[2:3], v[36:37]
	v_pk_fma_f32 v[10:11], v[4:5], v[38:39], v[10:11]
	v_pk_fma_f32 v[2:3], v[44:45], v[14:15], v[2:3] op_sel:[0,1,0]
	v_pk_fma_f32 v[10:11], v[6:7], v[40:41], v[10:11]
	v_pk_fma_f32 v[4:5], v[46:47], v[14:15], v[4:5] op_sel:[0,1,0]
	v_pk_fma_f32 v[10:11], v[8:9], v[42:43], v[10:11]
	v_pk_fma_f32 v[6:7], v[48:49], v[14:15], v[6:7] op_sel:[0,1,0]
	v_pk_fma_f32 v[10:11], v[14:15], v[142:143], v[10:11]
	v_pk_fma_f32 v[8:9], v[50:51], v[14:15], v[8:9] op_sel:[0,1,0]
	v_add_f32_e32 v10, v10, v11
	v_pk_fma_f32 v[2:3], v[52:53], v[14:15], v[2:3] op_sel_hi:[1,0,1]
	v_pk_fma_f32 v[4:5], v[54:55], v[14:15], v[4:5] op_sel_hi:[1,0,1]
	v_add_f32_dpp v10, v10, v10 quad_perm:[1,0,3,2] row_mask:0xf bank_mask:0xf
	v_pk_fma_f32 v[6:7], v[56:57], v[14:15], v[6:7] op_sel_hi:[1,0,1]
	v_pk_fma_f32 v[8:9], v[58:59], v[14:15], v[8:9] op_sel_hi:[1,0,1]
	v_add_f32_dpp v10, v10, v10 quad_perm:[2,3,0,1] row_mask:0xf bank_mask:0xf
	v_pk_mul_f32 v[12:13], v[2:3], v[60:61]
	v_pk_fma_f32 v[12:13], v[4:5], v[62:63], v[12:13]
	v_add_f32_dpp v16, v10, v10 row_half_mirror row_mask:0xf bank_mask:0xf
	v_pk_fma_f32 v[12:13], v[6:7], v[64:65], v[12:13]
	v_pk_fma_f32 v[12:13], v[8:9], v[66:67], v[12:13]
	v_add_f32_e32 v22, v12, v13
	ds_read_b128 v[36:39], v30 offset:25088
	ds_read_b128 v[40:43], v30 offset:25104
	ds_read_b128 v[44:47], v30 offset:16896
	ds_read_b128 v[48:51], v30 offset:16912
	ds_read_b128 v[52:55], v30 offset:33280
	ds_read_b128 v[56:59], v30 offset:33296
	ds_read_b128 v[60:63], v30 offset:512
	ds_read_b128 v[64:67], v30 offset:528
	ds_read_b32 v15, v31 offset:41216
	s_waitcnt lgkmcnt(9)
	v_pk_mul_f32 v[10:11], v[2:3], v[68:69]
	v_pk_fma_f32 v[10:11], v[4:5], v[70:71], v[10:11]
	v_pk_fma_f32 v[2:3], v[76:77], v[16:17], v[2:3] op_sel:[0,1,0]
	v_pk_fma_f32 v[10:11], v[6:7], v[72:73], v[10:11]
	v_pk_fma_f32 v[4:5], v[78:79], v[16:17], v[4:5] op_sel:[0,1,0]
	v_pk_fma_f32 v[10:11], v[8:9], v[74:75], v[10:11]
	v_pk_fma_f32 v[6:7], v[80:81], v[16:17], v[6:7] op_sel:[0,1,0]
	v_pk_fma_f32 v[10:11], v[16:17], v[144:145], v[10:11]
	v_pk_fma_f32 v[8:9], v[82:83], v[16:17], v[8:9] op_sel:[0,1,0]
	v_add_f32_e32 v10, v10, v11
	v_pk_fma_f32 v[2:3], v[84:85], v[16:17], v[2:3] op_sel_hi:[1,0,1]
	v_pk_fma_f32 v[4:5], v[86:87], v[16:17], v[4:5] op_sel_hi:[1,0,1]
	v_add_f32_dpp v10, v10, v10 quad_perm:[1,0,3,2] row_mask:0xf bank_mask:0xf
	v_pk_fma_f32 v[6:7], v[88:89], v[16:17], v[6:7] op_sel_hi:[1,0,1]
	v_pk_fma_f32 v[8:9], v[90:91], v[16:17], v[8:9] op_sel_hi:[1,0,1]
	v_add_f32_dpp v10, v10, v10 quad_perm:[2,3,0,1] row_mask:0xf bank_mask:0xf
	v_pk_mul_f32 v[12:13], v[2:3], v[134:135]
	v_pk_fma_f32 v[12:13], v[4:5], v[136:137], v[12:13]
	v_add_f32_dpp v14, v10, v10 row_half_mirror row_mask:0xf bank_mask:0xf
	v_pk_fma_f32 v[12:13], v[6:7], v[138:139], v[12:13]
	v_pk_fma_f32 v[12:13], v[8:9], v[140:141], v[12:13]
	v_add_f32_e32 v23, v12, v13
	ds_read_b128 v[68:71], v30 offset:25344
	ds_read_b128 v[72:75], v30 offset:25360
	ds_read_b128 v[76:79], v30 offset:17152
	ds_read_b128 v[80:83], v30 offset:17168
	ds_read_b128 v[84:87], v30 offset:33536
	ds_read_b128 v[88:91], v30 offset:33552
	ds_read_b128 v[134:137], v30 offset:768
	ds_read_b128 v[138:141], v30 offset:784
	ds_read_b32 v17, v31 offset:41344
	ds_read_b128 v[142:145], v32 offset:45088
	s_waitcnt lgkmcnt(10)
	v_pk_mul_f32 v[10:11], v[2:3], v[36:37]
	v_pk_fma_f32 v[10:11], v[4:5], v[38:39], v[10:11]
	v_pk_fma_f32 v[2:3], v[44:45], v[14:15], v[2:3] op_sel:[0,1,0]
	v_pk_fma_f32 v[10:11], v[6:7], v[40:41], v[10:11]
	v_pk_fma_f32 v[4:5], v[46:47], v[14:15], v[4:5] op_sel:[0,1,0]
	v_pk_fma_f32 v[10:11], v[8:9], v[42:43], v[10:11]
	v_pk_fma_f32 v[6:7], v[48:49], v[14:15], v[6:7] op_sel:[0,1,0]
	v_pk_fma_f32 v[10:11], v[14:15], v[146:147], v[10:11]
	v_pk_fma_f32 v[8:9], v[50:51], v[14:15], v[8:9] op_sel:[0,1,0]
	v_add_f32_e32 v10, v10, v11
	v_pk_fma_f32 v[2:3], v[52:53], v[14:15], v[2:3] op_sel_hi:[1,0,1]
	v_pk_fma_f32 v[4:5], v[54:55], v[14:15], v[4:5] op_sel_hi:[1,0,1]
	v_add_f32_dpp v10, v10, v10 quad_perm:[1,0,3,2] row_mask:0xf bank_mask:0xf
	v_pk_fma_f32 v[6:7], v[56:57], v[14:15], v[6:7] op_sel_hi:[1,0,1]
	v_pk_fma_f32 v[8:9], v[58:59], v[14:15], v[8:9] op_sel_hi:[1,0,1]
	v_add_f32_dpp v10, v10, v10 quad_perm:[2,3,0,1] row_mask:0xf bank_mask:0xf
	v_pk_mul_f32 v[12:13], v[2:3], v[60:61]
	v_pk_fma_f32 v[12:13], v[4:5], v[62:63], v[12:13]
	v_add_f32_dpp v16, v10, v10 row_half_mirror row_mask:0xf bank_mask:0xf
	v_pk_fma_f32 v[12:13], v[6:7], v[64:65], v[12:13]
	v_pk_fma_f32 v[12:13], v[8:9], v[66:67], v[12:13]
	v_add_f32_e32 v24, v12, v13
	ds_read_b128 v[36:39], v30 offset:25600
	ds_read_b128 v[40:43], v30 offset:25616
	ds_read_b128 v[44:47], v30 offset:17408
	ds_read_b128 v[48:51], v30 offset:17424
	ds_read_b128 v[52:55], v30 offset:33792
	ds_read_b128 v[56:59], v30 offset:33808
	ds_read_b128 v[60:63], v30 offset:1024
	ds_read_b128 v[64:67], v30 offset:1040
	ds_read_b32 v15, v31 offset:41472
	s_waitcnt lgkmcnt(9)
	v_pk_mul_f32 v[10:11], v[2:3], v[68:69]
	v_pk_fma_f32 v[10:11], v[4:5], v[70:71], v[10:11]
	v_pk_fma_f32 v[2:3], v[76:77], v[16:17], v[2:3] op_sel:[0,1,0]
	v_pk_fma_f32 v[10:11], v[6:7], v[72:73], v[10:11]
	v_pk_fma_f32 v[4:5], v[78:79], v[16:17], v[4:5] op_sel:[0,1,0]
	v_pk_fma_f32 v[10:11], v[8:9], v[74:75], v[10:11]
	v_pk_fma_f32 v[6:7], v[80:81], v[16:17], v[6:7] op_sel:[0,1,0]
	v_pk_fma_f32 v[10:11], v[16:17], v[148:149], v[10:11]
	v_pk_fma_f32 v[8:9], v[82:83], v[16:17], v[8:9] op_sel:[0,1,0]
	v_add_f32_e32 v10, v10, v11
	v_pk_fma_f32 v[2:3], v[84:85], v[16:17], v[2:3] op_sel_hi:[1,0,1]
	v_pk_fma_f32 v[4:5], v[86:87], v[16:17], v[4:5] op_sel_hi:[1,0,1]
	v_add_f32_dpp v10, v10, v10 quad_perm:[1,0,3,2] row_mask:0xf bank_mask:0xf
	v_pk_fma_f32 v[6:7], v[88:89], v[16:17], v[6:7] op_sel_hi:[1,0,1]
	v_pk_fma_f32 v[8:9], v[90:91], v[16:17], v[8:9] op_sel_hi:[1,0,1]
	v_add_f32_dpp v10, v10, v10 quad_perm:[2,3,0,1] row_mask:0xf bank_mask:0xf
	v_pk_mul_f32 v[12:13], v[2:3], v[134:135]
	v_pk_fma_f32 v[12:13], v[4:5], v[136:137], v[12:13]
	v_add_f32_dpp v14, v10, v10 row_half_mirror row_mask:0xf bank_mask:0xf
	v_pk_fma_f32 v[12:13], v[6:7], v[138:139], v[12:13]
	v_pk_fma_f32 v[12:13], v[8:9], v[140:141], v[12:13]
	v_add_f32_e32 v25, v12, v13
	ds_read_b128 v[68:71], v30 offset:25856
	ds_read_b128 v[72:75], v30 offset:25872
	ds_read_b128 v[76:79], v30 offset:17664
	ds_read_b128 v[80:83], v30 offset:17680
	ds_read_b128 v[84:87], v30 offset:34048
	ds_read_b128 v[88:91], v30 offset:34064
	ds_read_b128 v[134:137], v30 offset:1280
	ds_read_b128 v[138:141], v30 offset:1296
	ds_read_b32 v17, v31 offset:41600
	ds_read_b128 v[146:149], v32 offset:45104
	s_waitcnt lgkmcnt(10)
	v_pk_mul_f32 v[10:11], v[2:3], v[36:37]
	v_pk_fma_f32 v[10:11], v[4:5], v[38:39], v[10:11]
	v_cndmask_b32_e64 v26, v22, v23, s[6:7]
	v_cndmask_b32_e64 v27, v23, v22, s[6:7]
	v_pk_fma_f32 v[2:3], v[44:45], v[14:15], v[2:3] op_sel:[0,1,0]
	v_pk_fma_f32 v[10:11], v[6:7], v[40:41], v[10:11]
	v_cndmask_b32_e64 v29, v25, v24, s[6:7]
	v_cndmask_b32_e64 v28, v24, v25, s[6:7]
	v_pk_fma_f32 v[4:5], v[46:47], v[14:15], v[4:5] op_sel:[0,1,0]
	v_pk_fma_f32 v[10:11], v[8:9], v[42:43], v[10:11]
	v_add_f32_dpp v26, v27, v26 quad_perm:[1,0,3,2] row_mask:0xf bank_mask:0xf
	v_pk_fma_f32 v[6:7], v[48:49], v[14:15], v[6:7] op_sel:[0,1,0]
	v_add_f32_dpp v28, v29, v28 quad_perm:[1,0,3,2] row_mask:0xf bank_mask:0xf
	v_pk_fma_f32 v[10:11], v[14:15], v[142:143], v[10:11]
	v_pk_fma_f32 v[8:9], v[50:51], v[14:15], v[8:9] op_sel:[0,1,0]
	v_cndmask_b32_e64 v27, v26, v28, s[10:11]
	v_cndmask_b32_e64 v29, v28, v26, s[10:11]
	v_add_f32_e32 v10, v10, v11
	v_pk_fma_f32 v[2:3], v[52:53], v[14:15], v[2:3] op_sel_hi:[1,0,1]
	v_add_f32_dpp v27, v29, v27 quad_perm:[2,3,0,1] row_mask:0xf bank_mask:0xf
	v_pk_fma_f32 v[4:5], v[54:55], v[14:15], v[4:5] op_sel_hi:[1,0,1]
	v_add_f32_dpp v10, v10, v10 quad_perm:[1,0,3,2] row_mask:0xf bank_mask:0xf
	v_pk_fma_f32 v[6:7], v[56:57], v[14:15], v[6:7] op_sel_hi:[1,0,1]
	v_add_f32_dpp v27, v27, v27 row_shl:4 row_mask:0xf bank_mask:0xf
	v_pk_fma_f32 v[8:9], v[58:59], v[14:15], v[8:9] op_sel_hi:[1,0,1]
	v_add_f32_dpp v10, v10, v10 quad_perm:[2,3,0,1] row_mask:0xf bank_mask:0xf
	v_pk_mul_f32 v[12:13], v[2:3], v[60:61]
	v_pk_fma_f32 v[12:13], v[4:5], v[62:63], v[12:13]
	v_add_f32_dpp v16, v10, v10 row_half_mirror row_mask:0xf bank_mask:0xf
	ds_write_b32 v33, v27 offset:0
	v_pk_fma_f32 v[12:13], v[6:7], v[64:65], v[12:13]
	v_pk_fma_f32 v[12:13], v[8:9], v[66:67], v[12:13]
	v_add_f32_e32 v22, v12, v13
	ds_read_b128 v[36:39], v30 offset:26112
	ds_read_b128 v[40:43], v30 offset:26128
	ds_read_b128 v[44:47], v30 offset:17920
	ds_read_b128 v[48:51], v30 offset:17936
	ds_read_b128 v[52:55], v30 offset:34304
	ds_read_b128 v[56:59], v30 offset:34320
	ds_read_b128 v[60:63], v30 offset:1536
	ds_read_b128 v[64:67], v30 offset:1552
	ds_read_b32 v15, v31 offset:41728
	s_waitcnt lgkmcnt(9)
	v_pk_mul_f32 v[10:11], v[2:3], v[68:69]
	v_pk_fma_f32 v[10:11], v[4:5], v[70:71], v[10:11]
	v_pk_fma_f32 v[2:3], v[76:77], v[16:17], v[2:3] op_sel:[0,1,0]
	v_pk_fma_f32 v[10:11], v[6:7], v[72:73], v[10:11]
	v_pk_fma_f32 v[4:5], v[78:79], v[16:17], v[4:5] op_sel:[0,1,0]
	v_pk_fma_f32 v[10:11], v[8:9], v[74:75], v[10:11]
	v_pk_fma_f32 v[6:7], v[80:81], v[16:17], v[6:7] op_sel:[0,1,0]
	v_pk_fma_f32 v[10:11], v[16:17], v[144:145], v[10:11]
	v_pk_fma_f32 v[8:9], v[82:83], v[16:17], v[8:9] op_sel:[0,1,0]
	v_add_f32_e32 v10, v10, v11
	v_pk_fma_f32 v[2:3], v[84:85], v[16:17], v[2:3] op_sel_hi:[1,0,1]
	v_pk_fma_f32 v[4:5], v[86:87], v[16:17], v[4:5] op_sel_hi:[1,0,1]
	v_add_f32_dpp v10, v10, v10 quad_perm:[1,0,3,2] row_mask:0xf bank_mask:0xf
	v_pk_fma_f32 v[6:7], v[88:89], v[16:17], v[6:7] op_sel_hi:[1,0,1]
	v_pk_fma_f32 v[8:9], v[90:91], v[16:17], v[8:9] op_sel_hi:[1,0,1]
	v_add_f32_dpp v10, v10, v10 quad_perm:[2,3,0,1] row_mask:0xf bank_mask:0xf
	v_pk_mul_f32 v[12:13], v[2:3], v[134:135]
	v_pk_fma_f32 v[12:13], v[4:5], v[136:137], v[12:13]
	v_add_f32_dpp v14, v10, v10 row_half_mirror row_mask:0xf bank_mask:0xf
	v_pk_fma_f32 v[12:13], v[6:7], v[138:139], v[12:13]
	v_pk_fma_f32 v[12:13], v[8:9], v[140:141], v[12:13]
	v_add_f32_e32 v23, v12, v13
	ds_read_b128 v[68:71], v30 offset:26368
	ds_read_b128 v[72:75], v30 offset:26384
	ds_read_b128 v[76:79], v30 offset:18176
	ds_read_b128 v[80:83], v30 offset:18192
	ds_read_b128 v[84:87], v30 offset:34560
	ds_read_b128 v[88:91], v30 offset:34576
	ds_read_b128 v[134:137], v30 offset:1792
	ds_read_b128 v[138:141], v30 offset:1808
	ds_read_b32 v17, v31 offset:41856
	ds_read_b128 v[142:145], v32 offset:45120
	s_waitcnt lgkmcnt(10)
	v_pk_mul_f32 v[10:11], v[2:3], v[36:37]
	v_pk_fma_f32 v[10:11], v[4:5], v[38:39], v[10:11]
	v_pk_fma_f32 v[2:3], v[44:45], v[14:15], v[2:3] op_sel:[0,1,0]
	v_pk_fma_f32 v[10:11], v[6:7], v[40:41], v[10:11]
	v_pk_fma_f32 v[4:5], v[46:47], v[14:15], v[4:5] op_sel:[0,1,0]
	v_pk_fma_f32 v[10:11], v[8:9], v[42:43], v[10:11]
	v_pk_fma_f32 v[6:7], v[48:49], v[14:15], v[6:7] op_sel:[0,1,0]
	v_pk_fma_f32 v[10:11], v[14:15], v[146:147], v[10:11]
	v_pk_fma_f32 v[8:9], v[50:51], v[14:15], v[8:9] op_sel:[0,1,0]
	v_add_f32_e32 v10, v10, v11
	v_pk_fma_f32 v[2:3], v[52:53], v[14:15], v[2:3] op_sel_hi:[1,0,1]
	v_pk_fma_f32 v[4:5], v[54:55], v[14:15], v[4:5] op_sel_hi:[1,0,1]
	v_add_f32_dpp v10, v10, v10 quad_perm:[1,0,3,2] row_mask:0xf bank_mask:0xf
	v_pk_fma_f32 v[6:7], v[56:57], v[14:15], v[6:7] op_sel_hi:[1,0,1]
	v_pk_fma_f32 v[8:9], v[58:59], v[14:15], v[8:9] op_sel_hi:[1,0,1]
	v_add_f32_dpp v10, v10, v10 quad_perm:[2,3,0,1] row_mask:0xf bank_mask:0xf
	v_pk_mul_f32 v[12:13], v[2:3], v[60:61]
	v_pk_fma_f32 v[12:13], v[4:5], v[62:63], v[12:13]
	v_add_f32_dpp v16, v10, v10 row_half_mirror row_mask:0xf bank_mask:0xf
	v_pk_fma_f32 v[12:13], v[6:7], v[64:65], v[12:13]
	v_pk_fma_f32 v[12:13], v[8:9], v[66:67], v[12:13]
	v_add_f32_e32 v24, v12, v13
	ds_read_b128 v[36:39], v30 offset:26624
	ds_read_b128 v[40:43], v30 offset:26640
	ds_read_b128 v[44:47], v30 offset:18432
	ds_read_b128 v[48:51], v30 offset:18448
	ds_read_b128 v[52:55], v30 offset:34816
	ds_read_b128 v[56:59], v30 offset:34832
	ds_read_b128 v[60:63], v30 offset:2048
	ds_read_b128 v[64:67], v30 offset:2064
	ds_read_b32 v15, v31 offset:41984
	s_waitcnt lgkmcnt(9)
	v_pk_mul_f32 v[10:11], v[2:3], v[68:69]
	v_pk_fma_f32 v[10:11], v[4:5], v[70:71], v[10:11]
	v_pk_fma_f32 v[2:3], v[76:77], v[16:17], v[2:3] op_sel:[0,1,0]
	v_pk_fma_f32 v[10:11], v[6:7], v[72:73], v[10:11]
	v_pk_fma_f32 v[4:5], v[78:79], v[16:17], v[4:5] op_sel:[0,1,0]
	v_pk_fma_f32 v[10:11], v[8:9], v[74:75], v[10:11]
	v_pk_fma_f32 v[6:7], v[80:81], v[16:17], v[6:7] op_sel:[0,1,0]
	v_pk_fma_f32 v[10:11], v[16:17], v[148:149], v[10:11]
	v_pk_fma_f32 v[8:9], v[82:83], v[16:17], v[8:9] op_sel:[0,1,0]
	v_add_f32_e32 v10, v10, v11
	v_pk_fma_f32 v[2:3], v[84:85], v[16:17], v[2:3] op_sel_hi:[1,0,1]
	v_pk_fma_f32 v[4:5], v[86:87], v[16:17], v[4:5] op_sel_hi:[1,0,1]
	v_add_f32_dpp v10, v10, v10 quad_perm:[1,0,3,2] row_mask:0xf bank_mask:0xf
	v_pk_fma_f32 v[6:7], v[88:89], v[16:17], v[6:7] op_sel_hi:[1,0,1]
	v_pk_fma_f32 v[8:9], v[90:91], v[16:17], v[8:9] op_sel_hi:[1,0,1]
	v_add_f32_dpp v10, v10, v10 quad_perm:[2,3,0,1] row_mask:0xf bank_mask:0xf
	v_pk_mul_f32 v[12:13], v[2:3], v[134:135]
	v_pk_fma_f32 v[12:13], v[4:5], v[136:137], v[12:13]
	v_add_f32_dpp v14, v10, v10 row_half_mirror row_mask:0xf bank_mask:0xf
	v_pk_fma_f32 v[12:13], v[6:7], v[138:139], v[12:13]
	v_pk_fma_f32 v[12:13], v[8:9], v[140:141], v[12:13]
	v_add_f32_e32 v25, v12, v13
	ds_read_b128 v[68:71], v30 offset:26880
	ds_read_b128 v[72:75], v30 offset:26896
	ds_read_b128 v[76:79], v30 offset:18688
	ds_read_b128 v[80:83], v30 offset:18704
	ds_read_b128 v[84:87], v30 offset:35072
	ds_read_b128 v[88:91], v30 offset:35088
	ds_read_b128 v[134:137], v30 offset:2304
	ds_read_b128 v[138:141], v30 offset:2320
	ds_read_b32 v17, v31 offset:42112
	ds_read_b128 v[146:149], v32 offset:45136
	s_waitcnt lgkmcnt(10)
	v_pk_mul_f32 v[10:11], v[2:3], v[36:37]
	v_pk_fma_f32 v[10:11], v[4:5], v[38:39], v[10:11]
	v_cndmask_b32_e64 v26, v22, v23, s[6:7]
	v_cndmask_b32_e64 v27, v23, v22, s[6:7]
	v_pk_fma_f32 v[2:3], v[44:45], v[14:15], v[2:3] op_sel:[0,1,0]
	v_pk_fma_f32 v[10:11], v[6:7], v[40:41], v[10:11]
	v_cndmask_b32_e64 v29, v25, v24, s[6:7]
	v_cndmask_b32_e64 v28, v24, v25, s[6:7]
	v_pk_fma_f32 v[4:5], v[46:47], v[14:15], v[4:5] op_sel:[0,1,0]
	v_pk_fma_f32 v[10:11], v[8:9], v[42:43], v[10:11]
	v_add_f32_dpp v26, v27, v26 quad_perm:[1,0,3,2] row_mask:0xf bank_mask:0xf
	v_pk_fma_f32 v[6:7], v[48:49], v[14:15], v[6:7] op_sel:[0,1,0]
	v_add_f32_dpp v28, v29, v28 quad_perm:[1,0,3,2] row_mask:0xf bank_mask:0xf
	v_pk_fma_f32 v[10:11], v[14:15], v[142:143], v[10:11]
	v_pk_fma_f32 v[8:9], v[50:51], v[14:15], v[8:9] op_sel:[0,1,0]
	v_cndmask_b32_e64 v27, v26, v28, s[10:11]
	v_cndmask_b32_e64 v29, v28, v26, s[10:11]
	v_add_f32_e32 v10, v10, v11
	v_pk_fma_f32 v[2:3], v[52:53], v[14:15], v[2:3] op_sel_hi:[1,0,1]
	v_add_f32_dpp v27, v29, v27 quad_perm:[2,3,0,1] row_mask:0xf bank_mask:0xf
	v_pk_fma_f32 v[4:5], v[54:55], v[14:15], v[4:5] op_sel_hi:[1,0,1]
	v_add_f32_dpp v10, v10, v10 quad_perm:[1,0,3,2] row_mask:0xf bank_mask:0xf
	v_pk_fma_f32 v[6:7], v[56:57], v[14:15], v[6:7] op_sel_hi:[1,0,1]
	v_add_f32_dpp v27, v27, v27 row_shl:4 row_mask:0xf bank_mask:0xf
	v_pk_fma_f32 v[8:9], v[58:59], v[14:15], v[8:9] op_sel_hi:[1,0,1]
	v_add_f32_dpp v10, v10, v10 quad_perm:[2,3,0,1] row_mask:0xf bank_mask:0xf
	v_pk_mul_f32 v[12:13], v[2:3], v[60:61]
	v_pk_fma_f32 v[12:13], v[4:5], v[62:63], v[12:13]
	v_add_f32_dpp v16, v10, v10 row_half_mirror row_mask:0xf bank_mask:0xf
	ds_write_b32 v33, v27 offset:512
	v_pk_fma_f32 v[12:13], v[6:7], v[64:65], v[12:13]
	v_pk_fma_f32 v[12:13], v[8:9], v[66:67], v[12:13]
	v_add_f32_e32 v22, v12, v13
	ds_read_b128 v[36:39], v30 offset:27136
	ds_read_b128 v[40:43], v30 offset:27152
	ds_read_b128 v[44:47], v30 offset:18944
	ds_read_b128 v[48:51], v30 offset:18960
	ds_read_b128 v[52:55], v30 offset:35328
	ds_read_b128 v[56:59], v30 offset:35344
	ds_read_b128 v[60:63], v30 offset:2560
	ds_read_b128 v[64:67], v30 offset:2576
	ds_read_b32 v15, v31 offset:42240
	s_waitcnt lgkmcnt(9)
	v_pk_mul_f32 v[10:11], v[2:3], v[68:69]
	v_pk_fma_f32 v[10:11], v[4:5], v[70:71], v[10:11]
	v_pk_fma_f32 v[2:3], v[76:77], v[16:17], v[2:3] op_sel:[0,1,0]
	v_pk_fma_f32 v[10:11], v[6:7], v[72:73], v[10:11]
	v_pk_fma_f32 v[4:5], v[78:79], v[16:17], v[4:5] op_sel:[0,1,0]
	v_pk_fma_f32 v[10:11], v[8:9], v[74:75], v[10:11]
	v_pk_fma_f32 v[6:7], v[80:81], v[16:17], v[6:7] op_sel:[0,1,0]
	v_pk_fma_f32 v[10:11], v[16:17], v[144:145], v[10:11]
	v_pk_fma_f32 v[8:9], v[82:83], v[16:17], v[8:9] op_sel:[0,1,0]
	v_add_f32_e32 v10, v10, v11
	v_pk_fma_f32 v[2:3], v[84:85], v[16:17], v[2:3] op_sel_hi:[1,0,1]
	v_pk_fma_f32 v[4:5], v[86:87], v[16:17], v[4:5] op_sel_hi:[1,0,1]
	v_add_f32_dpp v10, v10, v10 quad_perm:[1,0,3,2] row_mask:0xf bank_mask:0xf
	v_pk_fma_f32 v[6:7], v[88:89], v[16:17], v[6:7] op_sel_hi:[1,0,1]
	v_pk_fma_f32 v[8:9], v[90:91], v[16:17], v[8:9] op_sel_hi:[1,0,1]
	v_add_f32_dpp v10, v10, v10 quad_perm:[2,3,0,1] row_mask:0xf bank_mask:0xf
	v_pk_mul_f32 v[12:13], v[2:3], v[134:135]
	v_pk_fma_f32 v[12:13], v[4:5], v[136:137], v[12:13]
	v_add_f32_dpp v14, v10, v10 row_half_mirror row_mask:0xf bank_mask:0xf
	v_pk_fma_f32 v[12:13], v[6:7], v[138:139], v[12:13]
	v_pk_fma_f32 v[12:13], v[8:9], v[140:141], v[12:13]
	v_add_f32_e32 v23, v12, v13
	ds_read_b128 v[68:71], v30 offset:27392
	ds_read_b128 v[72:75], v30 offset:27408
	ds_read_b128 v[76:79], v30 offset:19200
	ds_read_b128 v[80:83], v30 offset:19216
	ds_read_b128 v[84:87], v30 offset:35584
	ds_read_b128 v[88:91], v30 offset:35600
	ds_read_b128 v[134:137], v30 offset:2816
	ds_read_b128 v[138:141], v30 offset:2832
	ds_read_b32 v17, v31 offset:42368
	ds_read_b128 v[142:145], v32 offset:45152
	s_waitcnt lgkmcnt(10)
	v_pk_mul_f32 v[10:11], v[2:3], v[36:37]
	v_pk_fma_f32 v[10:11], v[4:5], v[38:39], v[10:11]
	v_pk_fma_f32 v[2:3], v[44:45], v[14:15], v[2:3] op_sel:[0,1,0]
	v_pk_fma_f32 v[10:11], v[6:7], v[40:41], v[10:11]
	v_pk_fma_f32 v[4:5], v[46:47], v[14:15], v[4:5] op_sel:[0,1,0]
	v_pk_fma_f32 v[10:11], v[8:9], v[42:43], v[10:11]
	v_pk_fma_f32 v[6:7], v[48:49], v[14:15], v[6:7] op_sel:[0,1,0]
	v_pk_fma_f32 v[10:11], v[14:15], v[146:147], v[10:11]
	v_pk_fma_f32 v[8:9], v[50:51], v[14:15], v[8:9] op_sel:[0,1,0]
	v_add_f32_e32 v10, v10, v11
	v_pk_fma_f32 v[2:3], v[52:53], v[14:15], v[2:3] op_sel_hi:[1,0,1]
	v_pk_fma_f32 v[4:5], v[54:55], v[14:15], v[4:5] op_sel_hi:[1,0,1]
	v_add_f32_dpp v10, v10, v10 quad_perm:[1,0,3,2] row_mask:0xf bank_mask:0xf
	v_pk_fma_f32 v[6:7], v[56:57], v[14:15], v[6:7] op_sel_hi:[1,0,1]
	v_pk_fma_f32 v[8:9], v[58:59], v[14:15], v[8:9] op_sel_hi:[1,0,1]
	v_add_f32_dpp v10, v10, v10 quad_perm:[2,3,0,1] row_mask:0xf bank_mask:0xf
	v_pk_mul_f32 v[12:13], v[2:3], v[60:61]
	v_pk_fma_f32 v[12:13], v[4:5], v[62:63], v[12:13]
	v_add_f32_dpp v16, v10, v10 row_half_mirror row_mask:0xf bank_mask:0xf
	v_pk_fma_f32 v[12:13], v[6:7], v[64:65], v[12:13]
	v_pk_fma_f32 v[12:13], v[8:9], v[66:67], v[12:13]
	v_add_f32_e32 v24, v12, v13
	ds_read_b128 v[36:39], v30 offset:27648
	ds_read_b128 v[40:43], v30 offset:27664
	ds_read_b128 v[44:47], v30 offset:19456
	ds_read_b128 v[48:51], v30 offset:19472
	ds_read_b128 v[52:55], v30 offset:35840
	ds_read_b128 v[56:59], v30 offset:35856
	ds_read_b128 v[60:63], v30 offset:3072
	ds_read_b128 v[64:67], v30 offset:3088
	ds_read_b32 v15, v31 offset:42496
	s_waitcnt lgkmcnt(9)
	v_pk_mul_f32 v[10:11], v[2:3], v[68:69]
	v_pk_fma_f32 v[10:11], v[4:5], v[70:71], v[10:11]
	v_pk_fma_f32 v[2:3], v[76:77], v[16:17], v[2:3] op_sel:[0,1,0]
	v_pk_fma_f32 v[10:11], v[6:7], v[72:73], v[10:11]
	v_pk_fma_f32 v[4:5], v[78:79], v[16:17], v[4:5] op_sel:[0,1,0]
	v_pk_fma_f32 v[10:11], v[8:9], v[74:75], v[10:11]
	v_pk_fma_f32 v[6:7], v[80:81], v[16:17], v[6:7] op_sel:[0,1,0]
	v_pk_fma_f32 v[10:11], v[16:17], v[148:149], v[10:11]
	v_pk_fma_f32 v[8:9], v[82:83], v[16:17], v[8:9] op_sel:[0,1,0]
	v_add_f32_e32 v10, v10, v11
	v_pk_fma_f32 v[2:3], v[84:85], v[16:17], v[2:3] op_sel_hi:[1,0,1]
	v_pk_fma_f32 v[4:5], v[86:87], v[16:17], v[4:5] op_sel_hi:[1,0,1]
	v_add_f32_dpp v10, v10, v10 quad_perm:[1,0,3,2] row_mask:0xf bank_mask:0xf
	v_pk_fma_f32 v[6:7], v[88:89], v[16:17], v[6:7] op_sel_hi:[1,0,1]
	v_pk_fma_f32 v[8:9], v[90:91], v[16:17], v[8:9] op_sel_hi:[1,0,1]
	v_add_f32_dpp v10, v10, v10 quad_perm:[2,3,0,1] row_mask:0xf bank_mask:0xf
	v_pk_mul_f32 v[12:13], v[2:3], v[134:135]
	v_pk_fma_f32 v[12:13], v[4:5], v[136:137], v[12:13]
	v_add_f32_dpp v14, v10, v10 row_half_mirror row_mask:0xf bank_mask:0xf
	v_pk_fma_f32 v[12:13], v[6:7], v[138:139], v[12:13]
	v_pk_fma_f32 v[12:13], v[8:9], v[140:141], v[12:13]
	v_add_f32_e32 v25, v12, v13
	ds_read_b128 v[68:71], v30 offset:27904
	ds_read_b128 v[72:75], v30 offset:27920
	ds_read_b128 v[76:79], v30 offset:19712
	ds_read_b128 v[80:83], v30 offset:19728
	ds_read_b128 v[84:87], v30 offset:36096
	ds_read_b128 v[88:91], v30 offset:36112
	ds_read_b128 v[134:137], v30 offset:3328
	ds_read_b128 v[138:141], v30 offset:3344
	ds_read_b32 v17, v31 offset:42624
	ds_read_b128 v[146:149], v32 offset:45168
	s_waitcnt lgkmcnt(10)
	v_pk_mul_f32 v[10:11], v[2:3], v[36:37]
	v_pk_fma_f32 v[10:11], v[4:5], v[38:39], v[10:11]
	v_cndmask_b32_e64 v26, v22, v23, s[6:7]
	v_cndmask_b32_e64 v27, v23, v22, s[6:7]
	v_pk_fma_f32 v[2:3], v[44:45], v[14:15], v[2:3] op_sel:[0,1,0]
	v_pk_fma_f32 v[10:11], v[6:7], v[40:41], v[10:11]
	v_cndmask_b32_e64 v29, v25, v24, s[6:7]
	v_cndmask_b32_e64 v28, v24, v25, s[6:7]
	v_pk_fma_f32 v[4:5], v[46:47], v[14:15], v[4:5] op_sel:[0,1,0]
	v_pk_fma_f32 v[10:11], v[8:9], v[42:43], v[10:11]
	v_add_f32_dpp v26, v27, v26 quad_perm:[1,0,3,2] row_mask:0xf bank_mask:0xf
	v_pk_fma_f32 v[6:7], v[48:49], v[14:15], v[6:7] op_sel:[0,1,0]
	v_add_f32_dpp v28, v29, v28 quad_perm:[1,0,3,2] row_mask:0xf bank_mask:0xf
	v_pk_fma_f32 v[10:11], v[14:15], v[142:143], v[10:11]
	v_pk_fma_f32 v[8:9], v[50:51], v[14:15], v[8:9] op_sel:[0,1,0]
	v_cndmask_b32_e64 v27, v26, v28, s[10:11]
	v_cndmask_b32_e64 v29, v28, v26, s[10:11]
	v_add_f32_e32 v10, v10, v11
	v_pk_fma_f32 v[2:3], v[52:53], v[14:15], v[2:3] op_sel_hi:[1,0,1]
	v_add_f32_dpp v27, v29, v27 quad_perm:[2,3,0,1] row_mask:0xf bank_mask:0xf
	v_pk_fma_f32 v[4:5], v[54:55], v[14:15], v[4:5] op_sel_hi:[1,0,1]
	v_add_f32_dpp v10, v10, v10 quad_perm:[1,0,3,2] row_mask:0xf bank_mask:0xf
	v_pk_fma_f32 v[6:7], v[56:57], v[14:15], v[6:7] op_sel_hi:[1,0,1]
	v_add_f32_dpp v27, v27, v27 row_shl:4 row_mask:0xf bank_mask:0xf
	v_pk_fma_f32 v[8:9], v[58:59], v[14:15], v[8:9] op_sel_hi:[1,0,1]
	v_add_f32_dpp v10, v10, v10 quad_perm:[2,3,0,1] row_mask:0xf bank_mask:0xf
	v_pk_mul_f32 v[12:13], v[2:3], v[60:61]
	v_pk_fma_f32 v[12:13], v[4:5], v[62:63], v[12:13]
	v_add_f32_dpp v16, v10, v10 row_half_mirror row_mask:0xf bank_mask:0xf
	ds_write_b32 v33, v27 offset:1024
	v_pk_fma_f32 v[12:13], v[6:7], v[64:65], v[12:13]
	v_pk_fma_f32 v[12:13], v[8:9], v[66:67], v[12:13]
	v_add_f32_e32 v22, v12, v13
	ds_read_b128 v[36:39], v30 offset:28160
	ds_read_b128 v[40:43], v30 offset:28176
	ds_read_b128 v[44:47], v30 offset:19968
	ds_read_b128 v[48:51], v30 offset:19984
	ds_read_b128 v[52:55], v30 offset:36352
	ds_read_b128 v[56:59], v30 offset:36368
	ds_read_b128 v[60:63], v30 offset:3584
	ds_read_b128 v[64:67], v30 offset:3600
	ds_read_b32 v15, v31 offset:42752
	s_waitcnt lgkmcnt(9)
	v_pk_mul_f32 v[10:11], v[2:3], v[68:69]
	v_pk_fma_f32 v[10:11], v[4:5], v[70:71], v[10:11]
	v_pk_fma_f32 v[2:3], v[76:77], v[16:17], v[2:3] op_sel:[0,1,0]
	v_pk_fma_f32 v[10:11], v[6:7], v[72:73], v[10:11]
	v_pk_fma_f32 v[4:5], v[78:79], v[16:17], v[4:5] op_sel:[0,1,0]
	v_pk_fma_f32 v[10:11], v[8:9], v[74:75], v[10:11]
	v_pk_fma_f32 v[6:7], v[80:81], v[16:17], v[6:7] op_sel:[0,1,0]
	v_pk_fma_f32 v[10:11], v[16:17], v[144:145], v[10:11]
	v_pk_fma_f32 v[8:9], v[82:83], v[16:17], v[8:9] op_sel:[0,1,0]
	v_add_f32_e32 v10, v10, v11
	v_pk_fma_f32 v[2:3], v[84:85], v[16:17], v[2:3] op_sel_hi:[1,0,1]
	v_pk_fma_f32 v[4:5], v[86:87], v[16:17], v[4:5] op_sel_hi:[1,0,1]
	v_add_f32_dpp v10, v10, v10 quad_perm:[1,0,3,2] row_mask:0xf bank_mask:0xf
	v_pk_fma_f32 v[6:7], v[88:89], v[16:17], v[6:7] op_sel_hi:[1,0,1]
	v_pk_fma_f32 v[8:9], v[90:91], v[16:17], v[8:9] op_sel_hi:[1,0,1]
	v_add_f32_dpp v10, v10, v10 quad_perm:[2,3,0,1] row_mask:0xf bank_mask:0xf
	v_pk_mul_f32 v[12:13], v[2:3], v[134:135]
	v_pk_fma_f32 v[12:13], v[4:5], v[136:137], v[12:13]
	v_add_f32_dpp v14, v10, v10 row_half_mirror row_mask:0xf bank_mask:0xf
	v_pk_fma_f32 v[12:13], v[6:7], v[138:139], v[12:13]
	v_pk_fma_f32 v[12:13], v[8:9], v[140:141], v[12:13]
	v_add_f32_e32 v23, v12, v13
	ds_read_b128 v[68:71], v30 offset:28416
	ds_read_b128 v[72:75], v30 offset:28432
	ds_read_b128 v[76:79], v30 offset:20224
	ds_read_b128 v[80:83], v30 offset:20240
	ds_read_b128 v[84:87], v30 offset:36608
	ds_read_b128 v[88:91], v30 offset:36624
	ds_read_b128 v[134:137], v30 offset:3840
	ds_read_b128 v[138:141], v30 offset:3856
	ds_read_b32 v17, v31 offset:42880
	ds_read_b128 v[142:145], v32 offset:45184
	s_waitcnt lgkmcnt(10)
	v_pk_mul_f32 v[10:11], v[2:3], v[36:37]
	v_pk_fma_f32 v[10:11], v[4:5], v[38:39], v[10:11]
	v_pk_fma_f32 v[2:3], v[44:45], v[14:15], v[2:3] op_sel:[0,1,0]
	v_pk_fma_f32 v[10:11], v[6:7], v[40:41], v[10:11]
	v_pk_fma_f32 v[4:5], v[46:47], v[14:15], v[4:5] op_sel:[0,1,0]
	v_pk_fma_f32 v[10:11], v[8:9], v[42:43], v[10:11]
	v_pk_fma_f32 v[6:7], v[48:49], v[14:15], v[6:7] op_sel:[0,1,0]
	v_pk_fma_f32 v[10:11], v[14:15], v[146:147], v[10:11]
	v_pk_fma_f32 v[8:9], v[50:51], v[14:15], v[8:9] op_sel:[0,1,0]
	v_add_f32_e32 v10, v10, v11
	v_pk_fma_f32 v[2:3], v[52:53], v[14:15], v[2:3] op_sel_hi:[1,0,1]
	v_pk_fma_f32 v[4:5], v[54:55], v[14:15], v[4:5] op_sel_hi:[1,0,1]
	v_add_f32_dpp v10, v10, v10 quad_perm:[1,0,3,2] row_mask:0xf bank_mask:0xf
	v_pk_fma_f32 v[6:7], v[56:57], v[14:15], v[6:7] op_sel_hi:[1,0,1]
	v_pk_fma_f32 v[8:9], v[58:59], v[14:15], v[8:9] op_sel_hi:[1,0,1]
	v_add_f32_dpp v10, v10, v10 quad_perm:[2,3,0,1] row_mask:0xf bank_mask:0xf
	v_pk_mul_f32 v[12:13], v[2:3], v[60:61]
	v_pk_fma_f32 v[12:13], v[4:5], v[62:63], v[12:13]
	v_add_f32_dpp v16, v10, v10 row_half_mirror row_mask:0xf bank_mask:0xf
	v_pk_fma_f32 v[12:13], v[6:7], v[64:65], v[12:13]
	v_pk_fma_f32 v[12:13], v[8:9], v[66:67], v[12:13]
	v_add_f32_e32 v24, v12, v13
	ds_read_b128 v[36:39], v30 offset:28672
	ds_read_b128 v[40:43], v30 offset:28688
	ds_read_b128 v[44:47], v30 offset:20480
	ds_read_b128 v[48:51], v30 offset:20496
	ds_read_b128 v[52:55], v30 offset:36864
	ds_read_b128 v[56:59], v30 offset:36880
	ds_read_b128 v[60:63], v30 offset:4096
	ds_read_b128 v[64:67], v30 offset:4112
	ds_read_b32 v15, v31 offset:43008
	s_waitcnt lgkmcnt(9)
	v_pk_mul_f32 v[10:11], v[2:3], v[68:69]
	v_pk_fma_f32 v[10:11], v[4:5], v[70:71], v[10:11]
	v_pk_fma_f32 v[2:3], v[76:77], v[16:17], v[2:3] op_sel:[0,1,0]
	v_pk_fma_f32 v[10:11], v[6:7], v[72:73], v[10:11]
	v_pk_fma_f32 v[4:5], v[78:79], v[16:17], v[4:5] op_sel:[0,1,0]
	v_pk_fma_f32 v[10:11], v[8:9], v[74:75], v[10:11]
	v_pk_fma_f32 v[6:7], v[80:81], v[16:17], v[6:7] op_sel:[0,1,0]
	v_pk_fma_f32 v[10:11], v[16:17], v[148:149], v[10:11]
	v_pk_fma_f32 v[8:9], v[82:83], v[16:17], v[8:9] op_sel:[0,1,0]
	v_add_f32_e32 v10, v10, v11
	v_pk_fma_f32 v[2:3], v[84:85], v[16:17], v[2:3] op_sel_hi:[1,0,1]
	v_pk_fma_f32 v[4:5], v[86:87], v[16:17], v[4:5] op_sel_hi:[1,0,1]
	v_add_f32_dpp v10, v10, v10 quad_perm:[1,0,3,2] row_mask:0xf bank_mask:0xf
	v_pk_fma_f32 v[6:7], v[88:89], v[16:17], v[6:7] op_sel_hi:[1,0,1]
	v_pk_fma_f32 v[8:9], v[90:91], v[16:17], v[8:9] op_sel_hi:[1,0,1]
	v_add_f32_dpp v10, v10, v10 quad_perm:[2,3,0,1] row_mask:0xf bank_mask:0xf
	v_pk_mul_f32 v[12:13], v[2:3], v[134:135]
	v_pk_fma_f32 v[12:13], v[4:5], v[136:137], v[12:13]
	v_add_f32_dpp v14, v10, v10 row_half_mirror row_mask:0xf bank_mask:0xf
	v_pk_fma_f32 v[12:13], v[6:7], v[138:139], v[12:13]
	v_pk_fma_f32 v[12:13], v[8:9], v[140:141], v[12:13]
	v_add_f32_e32 v25, v12, v13
	ds_read_b128 v[68:71], v30 offset:28928
	ds_read_b128 v[72:75], v30 offset:28944
	ds_read_b128 v[76:79], v30 offset:20736
	ds_read_b128 v[80:83], v30 offset:20752
	ds_read_b128 v[84:87], v30 offset:37120
	ds_read_b128 v[88:91], v30 offset:37136
	ds_read_b128 v[134:137], v30 offset:4352
	ds_read_b128 v[138:141], v30 offset:4368
	ds_read_b32 v17, v31 offset:43136
	ds_read_b128 v[146:149], v32 offset:45200
	s_waitcnt lgkmcnt(10)
	v_pk_mul_f32 v[10:11], v[2:3], v[36:37]
	v_pk_fma_f32 v[10:11], v[4:5], v[38:39], v[10:11]
	v_cndmask_b32_e64 v26, v22, v23, s[6:7]
	v_cndmask_b32_e64 v27, v23, v22, s[6:7]
	v_pk_fma_f32 v[2:3], v[44:45], v[14:15], v[2:3] op_sel:[0,1,0]
	v_pk_fma_f32 v[10:11], v[6:7], v[40:41], v[10:11]
	v_cndmask_b32_e64 v29, v25, v24, s[6:7]
	v_cndmask_b32_e64 v28, v24, v25, s[6:7]
	v_pk_fma_f32 v[4:5], v[46:47], v[14:15], v[4:5] op_sel:[0,1,0]
	v_pk_fma_f32 v[10:11], v[8:9], v[42:43], v[10:11]
	v_add_f32_dpp v26, v27, v26 quad_perm:[1,0,3,2] row_mask:0xf bank_mask:0xf
	v_pk_fma_f32 v[6:7], v[48:49], v[14:15], v[6:7] op_sel:[0,1,0]
	v_add_f32_dpp v28, v29, v28 quad_perm:[1,0,3,2] row_mask:0xf bank_mask:0xf
	v_pk_fma_f32 v[10:11], v[14:15], v[142:143], v[10:11]
	v_pk_fma_f32 v[8:9], v[50:51], v[14:15], v[8:9] op_sel:[0,1,0]
	v_cndmask_b32_e64 v27, v26, v28, s[10:11]
	v_cndmask_b32_e64 v29, v28, v26, s[10:11]
	v_add_f32_e32 v10, v10, v11
	v_pk_fma_f32 v[2:3], v[52:53], v[14:15], v[2:3] op_sel_hi:[1,0,1]
	v_add_f32_dpp v27, v29, v27 quad_perm:[2,3,0,1] row_mask:0xf bank_mask:0xf
	v_pk_fma_f32 v[4:5], v[54:55], v[14:15], v[4:5] op_sel_hi:[1,0,1]
	v_add_f32_dpp v10, v10, v10 quad_perm:[1,0,3,2] row_mask:0xf bank_mask:0xf
	v_pk_fma_f32 v[6:7], v[56:57], v[14:15], v[6:7] op_sel_hi:[1,0,1]
	v_add_f32_dpp v27, v27, v27 row_shl:4 row_mask:0xf bank_mask:0xf
	v_pk_fma_f32 v[8:9], v[58:59], v[14:15], v[8:9] op_sel_hi:[1,0,1]
	v_add_f32_dpp v10, v10, v10 quad_perm:[2,3,0,1] row_mask:0xf bank_mask:0xf
	v_pk_mul_f32 v[12:13], v[2:3], v[60:61]
	v_pk_fma_f32 v[12:13], v[4:5], v[62:63], v[12:13]
	v_add_f32_dpp v16, v10, v10 row_half_mirror row_mask:0xf bank_mask:0xf
	ds_write_b32 v33, v27 offset:1536
	v_pk_fma_f32 v[12:13], v[6:7], v[64:65], v[12:13]
	v_pk_fma_f32 v[12:13], v[8:9], v[66:67], v[12:13]
	v_add_f32_e32 v22, v12, v13
	ds_read_b128 v[36:39], v30 offset:29184
	ds_read_b128 v[40:43], v30 offset:29200
	ds_read_b128 v[44:47], v30 offset:20992
	ds_read_b128 v[48:51], v30 offset:21008
	ds_read_b128 v[52:55], v30 offset:37376
	ds_read_b128 v[56:59], v30 offset:37392
	ds_read_b128 v[60:63], v30 offset:4608
	ds_read_b128 v[64:67], v30 offset:4624
	ds_read_b32 v15, v31 offset:43264
	s_waitcnt lgkmcnt(9)
	v_pk_mul_f32 v[10:11], v[2:3], v[68:69]
	v_pk_fma_f32 v[10:11], v[4:5], v[70:71], v[10:11]
	v_pk_fma_f32 v[2:3], v[76:77], v[16:17], v[2:3] op_sel:[0,1,0]
	v_pk_fma_f32 v[10:11], v[6:7], v[72:73], v[10:11]
	v_pk_fma_f32 v[4:5], v[78:79], v[16:17], v[4:5] op_sel:[0,1,0]
	v_pk_fma_f32 v[10:11], v[8:9], v[74:75], v[10:11]
	v_pk_fma_f32 v[6:7], v[80:81], v[16:17], v[6:7] op_sel:[0,1,0]
	v_pk_fma_f32 v[10:11], v[16:17], v[144:145], v[10:11]
	v_pk_fma_f32 v[8:9], v[82:83], v[16:17], v[8:9] op_sel:[0,1,0]
	v_add_f32_e32 v10, v10, v11
	v_pk_fma_f32 v[2:3], v[84:85], v[16:17], v[2:3] op_sel_hi:[1,0,1]
	v_pk_fma_f32 v[4:5], v[86:87], v[16:17], v[4:5] op_sel_hi:[1,0,1]
	v_add_f32_dpp v10, v10, v10 quad_perm:[1,0,3,2] row_mask:0xf bank_mask:0xf
	v_pk_fma_f32 v[6:7], v[88:89], v[16:17], v[6:7] op_sel_hi:[1,0,1]
	v_pk_fma_f32 v[8:9], v[90:91], v[16:17], v[8:9] op_sel_hi:[1,0,1]
	v_add_f32_dpp v10, v10, v10 quad_perm:[2,3,0,1] row_mask:0xf bank_mask:0xf
	v_pk_mul_f32 v[12:13], v[2:3], v[134:135]
	v_pk_fma_f32 v[12:13], v[4:5], v[136:137], v[12:13]
	v_add_f32_dpp v14, v10, v10 row_half_mirror row_mask:0xf bank_mask:0xf
	v_pk_fma_f32 v[12:13], v[6:7], v[138:139], v[12:13]
	v_pk_fma_f32 v[12:13], v[8:9], v[140:141], v[12:13]
	v_add_f32_e32 v23, v12, v13
	ds_read_b128 v[68:71], v30 offset:29440
	ds_read_b128 v[72:75], v30 offset:29456
	ds_read_b128 v[76:79], v30 offset:21248
	ds_read_b128 v[80:83], v30 offset:21264
	ds_read_b128 v[84:87], v30 offset:37632
	ds_read_b128 v[88:91], v30 offset:37648
	ds_read_b128 v[134:137], v30 offset:4864
	ds_read_b128 v[138:141], v30 offset:4880
	ds_read_b32 v17, v31 offset:43392
	ds_read_b128 v[142:145], v32 offset:45216
	s_waitcnt lgkmcnt(10)
	v_pk_mul_f32 v[10:11], v[2:3], v[36:37]
	v_pk_fma_f32 v[10:11], v[4:5], v[38:39], v[10:11]
	v_pk_fma_f32 v[2:3], v[44:45], v[14:15], v[2:3] op_sel:[0,1,0]
	v_pk_fma_f32 v[10:11], v[6:7], v[40:41], v[10:11]
	v_pk_fma_f32 v[4:5], v[46:47], v[14:15], v[4:5] op_sel:[0,1,0]
	v_pk_fma_f32 v[10:11], v[8:9], v[42:43], v[10:11]
	v_pk_fma_f32 v[6:7], v[48:49], v[14:15], v[6:7] op_sel:[0,1,0]
	v_pk_fma_f32 v[10:11], v[14:15], v[146:147], v[10:11]
	v_pk_fma_f32 v[8:9], v[50:51], v[14:15], v[8:9] op_sel:[0,1,0]
	v_add_f32_e32 v10, v10, v11
	v_pk_fma_f32 v[2:3], v[52:53], v[14:15], v[2:3] op_sel_hi:[1,0,1]
	v_pk_fma_f32 v[4:5], v[54:55], v[14:15], v[4:5] op_sel_hi:[1,0,1]
	v_add_f32_dpp v10, v10, v10 quad_perm:[1,0,3,2] row_mask:0xf bank_mask:0xf
	v_pk_fma_f32 v[6:7], v[56:57], v[14:15], v[6:7] op_sel_hi:[1,0,1]
	v_pk_fma_f32 v[8:9], v[58:59], v[14:15], v[8:9] op_sel_hi:[1,0,1]
	v_add_f32_dpp v10, v10, v10 quad_perm:[2,3,0,1] row_mask:0xf bank_mask:0xf
	v_pk_mul_f32 v[12:13], v[2:3], v[60:61]
	v_pk_fma_f32 v[12:13], v[4:5], v[62:63], v[12:13]
	v_add_f32_dpp v16, v10, v10 row_half_mirror row_mask:0xf bank_mask:0xf
	v_pk_fma_f32 v[12:13], v[6:7], v[64:65], v[12:13]
	v_pk_fma_f32 v[12:13], v[8:9], v[66:67], v[12:13]
	v_add_f32_e32 v24, v12, v13
	ds_read_b128 v[36:39], v30 offset:29696
	ds_read_b128 v[40:43], v30 offset:29712
	ds_read_b128 v[44:47], v30 offset:21504
	ds_read_b128 v[48:51], v30 offset:21520
	ds_read_b128 v[52:55], v30 offset:37888
	ds_read_b128 v[56:59], v30 offset:37904
	ds_read_b128 v[60:63], v30 offset:5120
	ds_read_b128 v[64:67], v30 offset:5136
	ds_read_b32 v15, v31 offset:43520
	s_waitcnt lgkmcnt(9)
	v_pk_mul_f32 v[10:11], v[2:3], v[68:69]
	v_pk_fma_f32 v[10:11], v[4:5], v[70:71], v[10:11]
	v_pk_fma_f32 v[2:3], v[76:77], v[16:17], v[2:3] op_sel:[0,1,0]
	v_pk_fma_f32 v[10:11], v[6:7], v[72:73], v[10:11]
	v_pk_fma_f32 v[4:5], v[78:79], v[16:17], v[4:5] op_sel:[0,1,0]
	v_pk_fma_f32 v[10:11], v[8:9], v[74:75], v[10:11]
	v_pk_fma_f32 v[6:7], v[80:81], v[16:17], v[6:7] op_sel:[0,1,0]
	v_pk_fma_f32 v[10:11], v[16:17], v[148:149], v[10:11]
	v_pk_fma_f32 v[8:9], v[82:83], v[16:17], v[8:9] op_sel:[0,1,0]
	v_add_f32_e32 v10, v10, v11
	v_pk_fma_f32 v[2:3], v[84:85], v[16:17], v[2:3] op_sel_hi:[1,0,1]
	v_pk_fma_f32 v[4:5], v[86:87], v[16:17], v[4:5] op_sel_hi:[1,0,1]
	v_add_f32_dpp v10, v10, v10 quad_perm:[1,0,3,2] row_mask:0xf bank_mask:0xf
	v_pk_fma_f32 v[6:7], v[88:89], v[16:17], v[6:7] op_sel_hi:[1,0,1]
	v_pk_fma_f32 v[8:9], v[90:91], v[16:17], v[8:9] op_sel_hi:[1,0,1]
	v_add_f32_dpp v10, v10, v10 quad_perm:[2,3,0,1] row_mask:0xf bank_mask:0xf
	v_pk_mul_f32 v[12:13], v[2:3], v[134:135]
	v_pk_fma_f32 v[12:13], v[4:5], v[136:137], v[12:13]
	v_add_f32_dpp v14, v10, v10 row_half_mirror row_mask:0xf bank_mask:0xf
	v_pk_fma_f32 v[12:13], v[6:7], v[138:139], v[12:13]
	v_pk_fma_f32 v[12:13], v[8:9], v[140:141], v[12:13]
	v_add_f32_e32 v25, v12, v13
	ds_read_b128 v[68:71], v30 offset:29952
	ds_read_b128 v[72:75], v30 offset:29968
	ds_read_b128 v[76:79], v30 offset:21760
	ds_read_b128 v[80:83], v30 offset:21776
	ds_read_b128 v[84:87], v30 offset:38144
	ds_read_b128 v[88:91], v30 offset:38160
	ds_read_b128 v[134:137], v30 offset:5376
	ds_read_b128 v[138:141], v30 offset:5392
	ds_read_b32 v17, v31 offset:43648
	ds_read_b128 v[146:149], v32 offset:45232
	s_waitcnt lgkmcnt(10)
	v_pk_mul_f32 v[10:11], v[2:3], v[36:37]
	v_pk_fma_f32 v[10:11], v[4:5], v[38:39], v[10:11]
	v_cndmask_b32_e64 v26, v22, v23, s[6:7]
	v_cndmask_b32_e64 v27, v23, v22, s[6:7]
	v_pk_fma_f32 v[2:3], v[44:45], v[14:15], v[2:3] op_sel:[0,1,0]
	v_pk_fma_f32 v[10:11], v[6:7], v[40:41], v[10:11]
	v_cndmask_b32_e64 v29, v25, v24, s[6:7]
	v_cndmask_b32_e64 v28, v24, v25, s[6:7]
	v_pk_fma_f32 v[4:5], v[46:47], v[14:15], v[4:5] op_sel:[0,1,0]
	v_pk_fma_f32 v[10:11], v[8:9], v[42:43], v[10:11]
	v_add_f32_dpp v26, v27, v26 quad_perm:[1,0,3,2] row_mask:0xf bank_mask:0xf
	v_pk_fma_f32 v[6:7], v[48:49], v[14:15], v[6:7] op_sel:[0,1,0]
	v_add_f32_dpp v28, v29, v28 quad_perm:[1,0,3,2] row_mask:0xf bank_mask:0xf
	v_pk_fma_f32 v[10:11], v[14:15], v[142:143], v[10:11]
	v_pk_fma_f32 v[8:9], v[50:51], v[14:15], v[8:9] op_sel:[0,1,0]
	v_cndmask_b32_e64 v27, v26, v28, s[10:11]
	v_cndmask_b32_e64 v29, v28, v26, s[10:11]
	v_add_f32_e32 v10, v10, v11
	v_pk_fma_f32 v[2:3], v[52:53], v[14:15], v[2:3] op_sel_hi:[1,0,1]
	v_add_f32_dpp v27, v29, v27 quad_perm:[2,3,0,1] row_mask:0xf bank_mask:0xf
	v_pk_fma_f32 v[4:5], v[54:55], v[14:15], v[4:5] op_sel_hi:[1,0,1]
	v_add_f32_dpp v10, v10, v10 quad_perm:[1,0,3,2] row_mask:0xf bank_mask:0xf
	v_pk_fma_f32 v[6:7], v[56:57], v[14:15], v[6:7] op_sel_hi:[1,0,1]
	v_add_f32_dpp v27, v27, v27 row_shl:4 row_mask:0xf bank_mask:0xf
	v_pk_fma_f32 v[8:9], v[58:59], v[14:15], v[8:9] op_sel_hi:[1,0,1]
	v_add_f32_dpp v10, v10, v10 quad_perm:[2,3,0,1] row_mask:0xf bank_mask:0xf
	v_pk_mul_f32 v[12:13], v[2:3], v[60:61]
	v_pk_fma_f32 v[12:13], v[4:5], v[62:63], v[12:13]
	v_add_f32_dpp v16, v10, v10 row_half_mirror row_mask:0xf bank_mask:0xf
	ds_write_b32 v33, v27 offset:2048
	v_pk_fma_f32 v[12:13], v[6:7], v[64:65], v[12:13]
	v_pk_fma_f32 v[12:13], v[8:9], v[66:67], v[12:13]
	v_add_f32_e32 v22, v12, v13
	ds_read_b128 v[36:39], v30 offset:30208
	ds_read_b128 v[40:43], v30 offset:30224
	ds_read_b128 v[44:47], v30 offset:22016
	ds_read_b128 v[48:51], v30 offset:22032
	ds_read_b128 v[52:55], v30 offset:38400
	ds_read_b128 v[56:59], v30 offset:38416
	ds_read_b128 v[60:63], v30 offset:5632
	ds_read_b128 v[64:67], v30 offset:5648
	ds_read_b32 v15, v31 offset:43776
	s_waitcnt lgkmcnt(9)
	v_pk_mul_f32 v[10:11], v[2:3], v[68:69]
	v_pk_fma_f32 v[10:11], v[4:5], v[70:71], v[10:11]
	v_pk_fma_f32 v[2:3], v[76:77], v[16:17], v[2:3] op_sel:[0,1,0]
	v_pk_fma_f32 v[10:11], v[6:7], v[72:73], v[10:11]
	v_pk_fma_f32 v[4:5], v[78:79], v[16:17], v[4:5] op_sel:[0,1,0]
	v_pk_fma_f32 v[10:11], v[8:9], v[74:75], v[10:11]
	v_pk_fma_f32 v[6:7], v[80:81], v[16:17], v[6:7] op_sel:[0,1,0]
	v_pk_fma_f32 v[10:11], v[16:17], v[144:145], v[10:11]
	v_pk_fma_f32 v[8:9], v[82:83], v[16:17], v[8:9] op_sel:[0,1,0]
	v_add_f32_e32 v10, v10, v11
	v_pk_fma_f32 v[2:3], v[84:85], v[16:17], v[2:3] op_sel_hi:[1,0,1]
	v_pk_fma_f32 v[4:5], v[86:87], v[16:17], v[4:5] op_sel_hi:[1,0,1]
	v_add_f32_dpp v10, v10, v10 quad_perm:[1,0,3,2] row_mask:0xf bank_mask:0xf
	v_pk_fma_f32 v[6:7], v[88:89], v[16:17], v[6:7] op_sel_hi:[1,0,1]
	v_pk_fma_f32 v[8:9], v[90:91], v[16:17], v[8:9] op_sel_hi:[1,0,1]
	v_add_f32_dpp v10, v10, v10 quad_perm:[2,3,0,1] row_mask:0xf bank_mask:0xf
	v_pk_mul_f32 v[12:13], v[2:3], v[134:135]
	v_pk_fma_f32 v[12:13], v[4:5], v[136:137], v[12:13]
	v_add_f32_dpp v14, v10, v10 row_half_mirror row_mask:0xf bank_mask:0xf
	v_pk_fma_f32 v[12:13], v[6:7], v[138:139], v[12:13]
	v_pk_fma_f32 v[12:13], v[8:9], v[140:141], v[12:13]
	v_add_f32_e32 v23, v12, v13
	ds_read_b128 v[68:71], v30 offset:30464
	ds_read_b128 v[72:75], v30 offset:30480
	ds_read_b128 v[76:79], v30 offset:22272
	ds_read_b128 v[80:83], v30 offset:22288
	ds_read_b128 v[84:87], v30 offset:38656
	ds_read_b128 v[88:91], v30 offset:38672
	ds_read_b128 v[134:137], v30 offset:5888
	ds_read_b128 v[138:141], v30 offset:5904
	ds_read_b32 v17, v31 offset:43904
	ds_read_b128 v[142:145], v32 offset:45248
	s_waitcnt lgkmcnt(10)
	v_pk_mul_f32 v[10:11], v[2:3], v[36:37]
	v_pk_fma_f32 v[10:11], v[4:5], v[38:39], v[10:11]
	v_pk_fma_f32 v[2:3], v[44:45], v[14:15], v[2:3] op_sel:[0,1,0]
	v_pk_fma_f32 v[10:11], v[6:7], v[40:41], v[10:11]
	v_pk_fma_f32 v[4:5], v[46:47], v[14:15], v[4:5] op_sel:[0,1,0]
	v_pk_fma_f32 v[10:11], v[8:9], v[42:43], v[10:11]
	v_pk_fma_f32 v[6:7], v[48:49], v[14:15], v[6:7] op_sel:[0,1,0]
	v_pk_fma_f32 v[10:11], v[14:15], v[146:147], v[10:11]
	v_pk_fma_f32 v[8:9], v[50:51], v[14:15], v[8:9] op_sel:[0,1,0]
	v_add_f32_e32 v10, v10, v11
	v_pk_fma_f32 v[2:3], v[52:53], v[14:15], v[2:3] op_sel_hi:[1,0,1]
	v_pk_fma_f32 v[4:5], v[54:55], v[14:15], v[4:5] op_sel_hi:[1,0,1]
	v_add_f32_dpp v10, v10, v10 quad_perm:[1,0,3,2] row_mask:0xf bank_mask:0xf
	v_pk_fma_f32 v[6:7], v[56:57], v[14:15], v[6:7] op_sel_hi:[1,0,1]
	v_pk_fma_f32 v[8:9], v[58:59], v[14:15], v[8:9] op_sel_hi:[1,0,1]
	v_add_f32_dpp v10, v10, v10 quad_perm:[2,3,0,1] row_mask:0xf bank_mask:0xf
	v_pk_mul_f32 v[12:13], v[2:3], v[60:61]
	v_pk_fma_f32 v[12:13], v[4:5], v[62:63], v[12:13]
	v_add_f32_dpp v16, v10, v10 row_half_mirror row_mask:0xf bank_mask:0xf
	v_pk_fma_f32 v[12:13], v[6:7], v[64:65], v[12:13]
	v_pk_fma_f32 v[12:13], v[8:9], v[66:67], v[12:13]
	v_add_f32_e32 v24, v12, v13
	ds_read_b128 v[36:39], v30 offset:30720
	ds_read_b128 v[40:43], v30 offset:30736
	ds_read_b128 v[44:47], v30 offset:22528
	ds_read_b128 v[48:51], v30 offset:22544
	ds_read_b128 v[52:55], v30 offset:38912
	ds_read_b128 v[56:59], v30 offset:38928
	ds_read_b128 v[60:63], v30 offset:6144
	ds_read_b128 v[64:67], v30 offset:6160
	ds_read_b32 v15, v31 offset:44032
	s_waitcnt lgkmcnt(9)
	v_pk_mul_f32 v[10:11], v[2:3], v[68:69]
	v_pk_fma_f32 v[10:11], v[4:5], v[70:71], v[10:11]
	v_pk_fma_f32 v[2:3], v[76:77], v[16:17], v[2:3] op_sel:[0,1,0]
	v_pk_fma_f32 v[10:11], v[6:7], v[72:73], v[10:11]
	v_pk_fma_f32 v[4:5], v[78:79], v[16:17], v[4:5] op_sel:[0,1,0]
	v_pk_fma_f32 v[10:11], v[8:9], v[74:75], v[10:11]
	v_pk_fma_f32 v[6:7], v[80:81], v[16:17], v[6:7] op_sel:[0,1,0]
	v_pk_fma_f32 v[10:11], v[16:17], v[148:149], v[10:11]
	v_pk_fma_f32 v[8:9], v[82:83], v[16:17], v[8:9] op_sel:[0,1,0]
	v_add_f32_e32 v10, v10, v11
	v_pk_fma_f32 v[2:3], v[84:85], v[16:17], v[2:3] op_sel_hi:[1,0,1]
	v_pk_fma_f32 v[4:5], v[86:87], v[16:17], v[4:5] op_sel_hi:[1,0,1]
	v_add_f32_dpp v10, v10, v10 quad_perm:[1,0,3,2] row_mask:0xf bank_mask:0xf
	v_pk_fma_f32 v[6:7], v[88:89], v[16:17], v[6:7] op_sel_hi:[1,0,1]
	v_pk_fma_f32 v[8:9], v[90:91], v[16:17], v[8:9] op_sel_hi:[1,0,1]
	v_add_f32_dpp v10, v10, v10 quad_perm:[2,3,0,1] row_mask:0xf bank_mask:0xf
	v_pk_mul_f32 v[12:13], v[2:3], v[134:135]
	v_pk_fma_f32 v[12:13], v[4:5], v[136:137], v[12:13]
	v_add_f32_dpp v14, v10, v10 row_half_mirror row_mask:0xf bank_mask:0xf
	v_pk_fma_f32 v[12:13], v[6:7], v[138:139], v[12:13]
	v_pk_fma_f32 v[12:13], v[8:9], v[140:141], v[12:13]
	v_add_f32_e32 v25, v12, v13
	ds_read_b128 v[68:71], v30 offset:30976
	ds_read_b128 v[72:75], v30 offset:30992
	ds_read_b128 v[76:79], v30 offset:22784
	ds_read_b128 v[80:83], v30 offset:22800
	ds_read_b128 v[84:87], v30 offset:39168
	ds_read_b128 v[88:91], v30 offset:39184
	ds_read_b128 v[134:137], v30 offset:6400
	ds_read_b128 v[138:141], v30 offset:6416
	ds_read_b32 v17, v31 offset:44160
	ds_read_b128 v[146:149], v32 offset:45264
	s_waitcnt lgkmcnt(10)
	v_pk_mul_f32 v[10:11], v[2:3], v[36:37]
	v_pk_fma_f32 v[10:11], v[4:5], v[38:39], v[10:11]
	v_cndmask_b32_e64 v26, v22, v23, s[6:7]
	v_cndmask_b32_e64 v27, v23, v22, s[6:7]
	v_pk_fma_f32 v[2:3], v[44:45], v[14:15], v[2:3] op_sel:[0,1,0]
	v_pk_fma_f32 v[10:11], v[6:7], v[40:41], v[10:11]
	v_cndmask_b32_e64 v29, v25, v24, s[6:7]
	v_cndmask_b32_e64 v28, v24, v25, s[6:7]
	v_pk_fma_f32 v[4:5], v[46:47], v[14:15], v[4:5] op_sel:[0,1,0]
	v_pk_fma_f32 v[10:11], v[8:9], v[42:43], v[10:11]
	v_add_f32_dpp v26, v27, v26 quad_perm:[1,0,3,2] row_mask:0xf bank_mask:0xf
	v_pk_fma_f32 v[6:7], v[48:49], v[14:15], v[6:7] op_sel:[0,1,0]
	v_add_f32_dpp v28, v29, v28 quad_perm:[1,0,3,2] row_mask:0xf bank_mask:0xf
	v_pk_fma_f32 v[10:11], v[14:15], v[142:143], v[10:11]
	v_pk_fma_f32 v[8:9], v[50:51], v[14:15], v[8:9] op_sel:[0,1,0]
	v_cndmask_b32_e64 v27, v26, v28, s[10:11]
	v_cndmask_b32_e64 v29, v28, v26, s[10:11]
	v_add_f32_e32 v10, v10, v11
	v_pk_fma_f32 v[2:3], v[52:53], v[14:15], v[2:3] op_sel_hi:[1,0,1]
	v_add_f32_dpp v27, v29, v27 quad_perm:[2,3,0,1] row_mask:0xf bank_mask:0xf
	v_pk_fma_f32 v[4:5], v[54:55], v[14:15], v[4:5] op_sel_hi:[1,0,1]
	v_add_f32_dpp v10, v10, v10 quad_perm:[1,0,3,2] row_mask:0xf bank_mask:0xf
	v_pk_fma_f32 v[6:7], v[56:57], v[14:15], v[6:7] op_sel_hi:[1,0,1]
	v_add_f32_dpp v27, v27, v27 row_shl:4 row_mask:0xf bank_mask:0xf
	v_pk_fma_f32 v[8:9], v[58:59], v[14:15], v[8:9] op_sel_hi:[1,0,1]
	v_add_f32_dpp v10, v10, v10 quad_perm:[2,3,0,1] row_mask:0xf bank_mask:0xf
	v_pk_mul_f32 v[12:13], v[2:3], v[60:61]
	v_pk_fma_f32 v[12:13], v[4:5], v[62:63], v[12:13]
	v_add_f32_dpp v16, v10, v10 row_half_mirror row_mask:0xf bank_mask:0xf
	ds_write_b32 v33, v27 offset:2560
	v_pk_fma_f32 v[12:13], v[6:7], v[64:65], v[12:13]
	v_pk_fma_f32 v[12:13], v[8:9], v[66:67], v[12:13]
	v_add_f32_e32 v22, v12, v13
	ds_read_b128 v[36:39], v30 offset:31232
	ds_read_b128 v[40:43], v30 offset:31248
	ds_read_b128 v[44:47], v30 offset:23040
	ds_read_b128 v[48:51], v30 offset:23056
	ds_read_b128 v[52:55], v30 offset:39424
	ds_read_b128 v[56:59], v30 offset:39440
	ds_read_b128 v[60:63], v30 offset:6656
	ds_read_b128 v[64:67], v30 offset:6672
	ds_read_b32 v15, v31 offset:44288
	s_waitcnt lgkmcnt(9)
	v_pk_mul_f32 v[10:11], v[2:3], v[68:69]
	v_pk_fma_f32 v[10:11], v[4:5], v[70:71], v[10:11]
	v_pk_fma_f32 v[2:3], v[76:77], v[16:17], v[2:3] op_sel:[0,1,0]
	v_pk_fma_f32 v[10:11], v[6:7], v[72:73], v[10:11]
	v_pk_fma_f32 v[4:5], v[78:79], v[16:17], v[4:5] op_sel:[0,1,0]
	v_pk_fma_f32 v[10:11], v[8:9], v[74:75], v[10:11]
	v_pk_fma_f32 v[6:7], v[80:81], v[16:17], v[6:7] op_sel:[0,1,0]
	v_pk_fma_f32 v[10:11], v[16:17], v[144:145], v[10:11]
	v_pk_fma_f32 v[8:9], v[82:83], v[16:17], v[8:9] op_sel:[0,1,0]
	v_add_f32_e32 v10, v10, v11
	v_pk_fma_f32 v[2:3], v[84:85], v[16:17], v[2:3] op_sel_hi:[1,0,1]
	v_pk_fma_f32 v[4:5], v[86:87], v[16:17], v[4:5] op_sel_hi:[1,0,1]
	v_add_f32_dpp v10, v10, v10 quad_perm:[1,0,3,2] row_mask:0xf bank_mask:0xf
	v_pk_fma_f32 v[6:7], v[88:89], v[16:17], v[6:7] op_sel_hi:[1,0,1]
	v_pk_fma_f32 v[8:9], v[90:91], v[16:17], v[8:9] op_sel_hi:[1,0,1]
	v_add_f32_dpp v10, v10, v10 quad_perm:[2,3,0,1] row_mask:0xf bank_mask:0xf
	v_pk_mul_f32 v[12:13], v[2:3], v[134:135]
	v_pk_fma_f32 v[12:13], v[4:5], v[136:137], v[12:13]
	v_add_f32_dpp v14, v10, v10 row_half_mirror row_mask:0xf bank_mask:0xf
	v_pk_fma_f32 v[12:13], v[6:7], v[138:139], v[12:13]
	v_pk_fma_f32 v[12:13], v[8:9], v[140:141], v[12:13]
	v_add_f32_e32 v23, v12, v13
	ds_read_b128 v[68:71], v30 offset:31488
	ds_read_b128 v[72:75], v30 offset:31504
	ds_read_b128 v[76:79], v30 offset:23296
	ds_read_b128 v[80:83], v30 offset:23312
	ds_read_b128 v[84:87], v30 offset:39680
	ds_read_b128 v[88:91], v30 offset:39696
	ds_read_b128 v[134:137], v30 offset:6912
	ds_read_b128 v[138:141], v30 offset:6928
	ds_read_b32 v17, v31 offset:44416
	ds_read_b128 v[142:145], v32 offset:45280
	s_waitcnt lgkmcnt(10)
	v_pk_mul_f32 v[10:11], v[2:3], v[36:37]
	v_pk_fma_f32 v[10:11], v[4:5], v[38:39], v[10:11]
	v_pk_fma_f32 v[2:3], v[44:45], v[14:15], v[2:3] op_sel:[0,1,0]
	v_pk_fma_f32 v[10:11], v[6:7], v[40:41], v[10:11]
	v_pk_fma_f32 v[4:5], v[46:47], v[14:15], v[4:5] op_sel:[0,1,0]
	v_pk_fma_f32 v[10:11], v[8:9], v[42:43], v[10:11]
	v_pk_fma_f32 v[6:7], v[48:49], v[14:15], v[6:7] op_sel:[0,1,0]
	v_pk_fma_f32 v[10:11], v[14:15], v[146:147], v[10:11]
	v_pk_fma_f32 v[8:9], v[50:51], v[14:15], v[8:9] op_sel:[0,1,0]
	v_add_f32_e32 v10, v10, v11
	v_pk_fma_f32 v[2:3], v[52:53], v[14:15], v[2:3] op_sel_hi:[1,0,1]
	v_pk_fma_f32 v[4:5], v[54:55], v[14:15], v[4:5] op_sel_hi:[1,0,1]
	v_add_f32_dpp v10, v10, v10 quad_perm:[1,0,3,2] row_mask:0xf bank_mask:0xf
	v_pk_fma_f32 v[6:7], v[56:57], v[14:15], v[6:7] op_sel_hi:[1,0,1]
	v_pk_fma_f32 v[8:9], v[58:59], v[14:15], v[8:9] op_sel_hi:[1,0,1]
	v_add_f32_dpp v10, v10, v10 quad_perm:[2,3,0,1] row_mask:0xf bank_mask:0xf
	v_pk_mul_f32 v[12:13], v[2:3], v[60:61]
	v_pk_fma_f32 v[12:13], v[4:5], v[62:63], v[12:13]
	v_add_f32_dpp v16, v10, v10 row_half_mirror row_mask:0xf bank_mask:0xf
	v_pk_fma_f32 v[12:13], v[6:7], v[64:65], v[12:13]
	v_pk_fma_f32 v[12:13], v[8:9], v[66:67], v[12:13]
	v_add_f32_e32 v24, v12, v13
	ds_read_b128 v[36:39], v30 offset:31744
	ds_read_b128 v[40:43], v30 offset:31760
	ds_read_b128 v[44:47], v30 offset:23552
	ds_read_b128 v[48:51], v30 offset:23568
	ds_read_b128 v[52:55], v30 offset:39936
	ds_read_b128 v[56:59], v30 offset:39952
	ds_read_b128 v[60:63], v30 offset:7168
	ds_read_b128 v[64:67], v30 offset:7184
	ds_read_b32 v15, v31 offset:44544
	s_waitcnt lgkmcnt(9)
	v_pk_mul_f32 v[10:11], v[2:3], v[68:69]
	v_pk_fma_f32 v[10:11], v[4:5], v[70:71], v[10:11]
	v_pk_fma_f32 v[2:3], v[76:77], v[16:17], v[2:3] op_sel:[0,1,0]
	v_pk_fma_f32 v[10:11], v[6:7], v[72:73], v[10:11]
	v_pk_fma_f32 v[4:5], v[78:79], v[16:17], v[4:5] op_sel:[0,1,0]
	v_pk_fma_f32 v[10:11], v[8:9], v[74:75], v[10:11]
	v_pk_fma_f32 v[6:7], v[80:81], v[16:17], v[6:7] op_sel:[0,1,0]
	v_pk_fma_f32 v[10:11], v[16:17], v[148:149], v[10:11]
	v_pk_fma_f32 v[8:9], v[82:83], v[16:17], v[8:9] op_sel:[0,1,0]
	v_add_f32_e32 v10, v10, v11
	v_pk_fma_f32 v[2:3], v[84:85], v[16:17], v[2:3] op_sel_hi:[1,0,1]
	v_pk_fma_f32 v[4:5], v[86:87], v[16:17], v[4:5] op_sel_hi:[1,0,1]
	v_add_f32_dpp v10, v10, v10 quad_perm:[1,0,3,2] row_mask:0xf bank_mask:0xf
	v_pk_fma_f32 v[6:7], v[88:89], v[16:17], v[6:7] op_sel_hi:[1,0,1]
	v_pk_fma_f32 v[8:9], v[90:91], v[16:17], v[8:9] op_sel_hi:[1,0,1]
	v_add_f32_dpp v10, v10, v10 quad_perm:[2,3,0,1] row_mask:0xf bank_mask:0xf
	v_pk_mul_f32 v[12:13], v[2:3], v[134:135]
	v_pk_fma_f32 v[12:13], v[4:5], v[136:137], v[12:13]
	v_add_f32_dpp v14, v10, v10 row_half_mirror row_mask:0xf bank_mask:0xf
	v_pk_fma_f32 v[12:13], v[6:7], v[138:139], v[12:13]
	v_pk_fma_f32 v[12:13], v[8:9], v[140:141], v[12:13]
	v_add_f32_e32 v25, v12, v13
	ds_read_b128 v[68:71], v30 offset:32000
	ds_read_b128 v[72:75], v30 offset:32016
	ds_read_b128 v[76:79], v30 offset:23808
	ds_read_b128 v[80:83], v30 offset:23824
	ds_read_b128 v[84:87], v30 offset:40192
	ds_read_b128 v[88:91], v30 offset:40208
	ds_read_b128 v[134:137], v30 offset:7424
	ds_read_b128 v[138:141], v30 offset:7440
	ds_read_b32 v17, v31 offset:44672
	ds_read_b128 v[146:149], v32 offset:45296
	s_waitcnt lgkmcnt(10)
	v_pk_mul_f32 v[10:11], v[2:3], v[36:37]
	v_pk_fma_f32 v[10:11], v[4:5], v[38:39], v[10:11]
	v_cndmask_b32_e64 v26, v22, v23, s[6:7]
	v_cndmask_b32_e64 v27, v23, v22, s[6:7]
	v_pk_fma_f32 v[2:3], v[44:45], v[14:15], v[2:3] op_sel:[0,1,0]
	v_pk_fma_f32 v[10:11], v[6:7], v[40:41], v[10:11]
	v_cndmask_b32_e64 v29, v25, v24, s[6:7]
	v_cndmask_b32_e64 v28, v24, v25, s[6:7]
	v_pk_fma_f32 v[4:5], v[46:47], v[14:15], v[4:5] op_sel:[0,1,0]
	v_pk_fma_f32 v[10:11], v[8:9], v[42:43], v[10:11]
	v_add_f32_dpp v26, v27, v26 quad_perm:[1,0,3,2] row_mask:0xf bank_mask:0xf
	v_pk_fma_f32 v[6:7], v[48:49], v[14:15], v[6:7] op_sel:[0,1,0]
	v_add_f32_dpp v28, v29, v28 quad_perm:[1,0,3,2] row_mask:0xf bank_mask:0xf
	v_pk_fma_f32 v[10:11], v[14:15], v[142:143], v[10:11]
	v_pk_fma_f32 v[8:9], v[50:51], v[14:15], v[8:9] op_sel:[0,1,0]
	v_cndmask_b32_e64 v27, v26, v28, s[10:11]
	v_cndmask_b32_e64 v29, v28, v26, s[10:11]
	v_add_f32_e32 v10, v10, v11
	v_pk_fma_f32 v[2:3], v[52:53], v[14:15], v[2:3] op_sel_hi:[1,0,1]
	v_add_f32_dpp v27, v29, v27 quad_perm:[2,3,0,1] row_mask:0xf bank_mask:0xf
	v_pk_fma_f32 v[4:5], v[54:55], v[14:15], v[4:5] op_sel_hi:[1,0,1]
	v_add_f32_dpp v10, v10, v10 quad_perm:[1,0,3,2] row_mask:0xf bank_mask:0xf
	v_pk_fma_f32 v[6:7], v[56:57], v[14:15], v[6:7] op_sel_hi:[1,0,1]
	v_add_f32_dpp v27, v27, v27 row_shl:4 row_mask:0xf bank_mask:0xf
	v_pk_fma_f32 v[8:9], v[58:59], v[14:15], v[8:9] op_sel_hi:[1,0,1]
	v_add_f32_dpp v10, v10, v10 quad_perm:[2,3,0,1] row_mask:0xf bank_mask:0xf
	v_pk_mul_f32 v[12:13], v[2:3], v[60:61]
	v_pk_fma_f32 v[12:13], v[4:5], v[62:63], v[12:13]
	v_add_f32_dpp v16, v10, v10 row_half_mirror row_mask:0xf bank_mask:0xf
	ds_write_b32 v33, v27 offset:3072
	v_pk_fma_f32 v[12:13], v[6:7], v[64:65], v[12:13]
	v_pk_fma_f32 v[12:13], v[8:9], v[66:67], v[12:13]
	v_add_f32_e32 v22, v12, v13
	ds_read_b128 v[36:39], v30 offset:32256
	ds_read_b128 v[40:43], v30 offset:32272
	ds_read_b128 v[44:47], v30 offset:24064
	ds_read_b128 v[48:51], v30 offset:24080
	ds_read_b128 v[52:55], v30 offset:40448
	ds_read_b128 v[56:59], v30 offset:40464
	ds_read_b128 v[60:63], v30 offset:7680
	ds_read_b128 v[64:67], v30 offset:7696
	ds_read_b32 v15, v31 offset:44800
	s_waitcnt lgkmcnt(9)
	v_pk_mul_f32 v[10:11], v[2:3], v[68:69]
	v_pk_fma_f32 v[10:11], v[4:5], v[70:71], v[10:11]
	v_pk_fma_f32 v[2:3], v[76:77], v[16:17], v[2:3] op_sel:[0,1,0]
	v_pk_fma_f32 v[10:11], v[6:7], v[72:73], v[10:11]
	v_pk_fma_f32 v[4:5], v[78:79], v[16:17], v[4:5] op_sel:[0,1,0]
	v_pk_fma_f32 v[10:11], v[8:9], v[74:75], v[10:11]
	v_pk_fma_f32 v[6:7], v[80:81], v[16:17], v[6:7] op_sel:[0,1,0]
	v_pk_fma_f32 v[10:11], v[16:17], v[144:145], v[10:11]
	v_pk_fma_f32 v[8:9], v[82:83], v[16:17], v[8:9] op_sel:[0,1,0]
	v_add_f32_e32 v10, v10, v11
	v_pk_fma_f32 v[2:3], v[84:85], v[16:17], v[2:3] op_sel_hi:[1,0,1]
	v_pk_fma_f32 v[4:5], v[86:87], v[16:17], v[4:5] op_sel_hi:[1,0,1]
	v_add_f32_dpp v10, v10, v10 quad_perm:[1,0,3,2] row_mask:0xf bank_mask:0xf
	v_pk_fma_f32 v[6:7], v[88:89], v[16:17], v[6:7] op_sel_hi:[1,0,1]
	v_pk_fma_f32 v[8:9], v[90:91], v[16:17], v[8:9] op_sel_hi:[1,0,1]
	v_add_f32_dpp v10, v10, v10 quad_perm:[2,3,0,1] row_mask:0xf bank_mask:0xf
	v_pk_mul_f32 v[12:13], v[2:3], v[134:135]
	v_pk_fma_f32 v[12:13], v[4:5], v[136:137], v[12:13]
	v_add_f32_dpp v14, v10, v10 row_half_mirror row_mask:0xf bank_mask:0xf
	v_pk_fma_f32 v[12:13], v[6:7], v[138:139], v[12:13]
	v_pk_fma_f32 v[12:13], v[8:9], v[140:141], v[12:13]
	v_add_f32_e32 v23, v12, v13
	ds_read_b128 v[68:71], v30 offset:32512
	ds_read_b128 v[72:75], v30 offset:32528
	ds_read_b128 v[76:79], v30 offset:24320
	ds_read_b128 v[80:83], v30 offset:24336
	ds_read_b128 v[84:87], v30 offset:40704
	ds_read_b128 v[88:91], v30 offset:40720
	ds_read_b128 v[134:137], v30 offset:7936
	ds_read_b128 v[138:141], v30 offset:7952
	ds_read_b32 v17, v31 offset:44928
	s_waitcnt lgkmcnt(9)
	v_pk_mul_f32 v[10:11], v[2:3], v[36:37]
	v_pk_fma_f32 v[10:11], v[4:5], v[38:39], v[10:11]
	v_pk_fma_f32 v[2:3], v[44:45], v[14:15], v[2:3] op_sel:[0,1,0]
	v_pk_fma_f32 v[10:11], v[6:7], v[40:41], v[10:11]
	v_pk_fma_f32 v[4:5], v[46:47], v[14:15], v[4:5] op_sel:[0,1,0]
	v_pk_fma_f32 v[10:11], v[8:9], v[42:43], v[10:11]
	v_pk_fma_f32 v[6:7], v[48:49], v[14:15], v[6:7] op_sel:[0,1,0]
	v_pk_fma_f32 v[10:11], v[14:15], v[146:147], v[10:11]
	v_pk_fma_f32 v[8:9], v[50:51], v[14:15], v[8:9] op_sel:[0,1,0]
	v_add_f32_e32 v10, v10, v11
	v_pk_fma_f32 v[2:3], v[52:53], v[14:15], v[2:3] op_sel_hi:[1,0,1]
	v_pk_fma_f32 v[4:5], v[54:55], v[14:15], v[4:5] op_sel_hi:[1,0,1]
	v_add_f32_dpp v10, v10, v10 quad_perm:[1,0,3,2] row_mask:0xf bank_mask:0xf
	v_pk_fma_f32 v[6:7], v[56:57], v[14:15], v[6:7] op_sel_hi:[1,0,1]
	v_pk_fma_f32 v[8:9], v[58:59], v[14:15], v[8:9] op_sel_hi:[1,0,1]
	v_add_f32_dpp v10, v10, v10 quad_perm:[2,3,0,1] row_mask:0xf bank_mask:0xf
	v_pk_mul_f32 v[12:13], v[2:3], v[60:61]
	v_pk_fma_f32 v[12:13], v[4:5], v[62:63], v[12:13]
	v_add_f32_dpp v16, v10, v10 row_half_mirror row_mask:0xf bank_mask:0xf
	v_pk_fma_f32 v[12:13], v[6:7], v[64:65], v[12:13]
	v_pk_fma_f32 v[12:13], v[8:9], v[66:67], v[12:13]
	v_add_f32_e32 v24, v12, v13
	ds_read_b128 v[36:39], v30 offset:8192
	ds_read_b128 v[40:43], v30 offset:8208
	s_waitcnt lgkmcnt(2)
	v_pk_mul_f32 v[10:11], v[2:3], v[68:69]
	v_pk_fma_f32 v[10:11], v[4:5], v[70:71], v[10:11]
	v_pk_fma_f32 v[2:3], v[76:77], v[16:17], v[2:3] op_sel:[0,1,0]
	v_pk_fma_f32 v[10:11], v[6:7], v[72:73], v[10:11]
	v_pk_fma_f32 v[4:5], v[78:79], v[16:17], v[4:5] op_sel:[0,1,0]
	v_pk_fma_f32 v[10:11], v[8:9], v[74:75], v[10:11]
	v_pk_fma_f32 v[6:7], v[80:81], v[16:17], v[6:7] op_sel:[0,1,0]
	v_pk_fma_f32 v[10:11], v[16:17], v[148:149], v[10:11]
	v_pk_fma_f32 v[8:9], v[82:83], v[16:17], v[8:9] op_sel:[0,1,0]
	v_add_f32_e32 v10, v10, v11
	v_pk_fma_f32 v[2:3], v[84:85], v[16:17], v[2:3] op_sel_hi:[1,0,1]
	v_pk_fma_f32 v[4:5], v[86:87], v[16:17], v[4:5] op_sel_hi:[1,0,1]
	v_add_f32_dpp v10, v10, v10 quad_perm:[1,0,3,2] row_mask:0xf bank_mask:0xf
	v_pk_fma_f32 v[6:7], v[88:89], v[16:17], v[6:7] op_sel_hi:[1,0,1]
	v_pk_fma_f32 v[8:9], v[90:91], v[16:17], v[8:9] op_sel_hi:[1,0,1]
	v_add_f32_dpp v10, v10, v10 quad_perm:[2,3,0,1] row_mask:0xf bank_mask:0xf
	v_pk_mul_f32 v[12:13], v[2:3], v[134:135]
	v_pk_fma_f32 v[12:13], v[4:5], v[136:137], v[12:13]
	v_add_f32_dpp v14, v10, v10 row_half_mirror row_mask:0xf bank_mask:0xf
	v_pk_fma_f32 v[12:13], v[6:7], v[138:139], v[12:13]
	v_pk_fma_f32 v[12:13], v[8:9], v[140:141], v[12:13]
	v_add_f32_e32 v25, v12, v13
	v_cndmask_b32_e64 v26, v22, v23, s[6:7]
	v_cndmask_b32_e64 v27, v23, v22, s[6:7]
	v_cndmask_b32_e64 v29, v25, v24, s[6:7]
	v_cndmask_b32_e64 v28, v24, v25, s[6:7]
	v_add_f32_dpp v26, v27, v26 quad_perm:[1,0,3,2] row_mask:0xf bank_mask:0xf
	v_add_f32_dpp v28, v29, v28 quad_perm:[1,0,3,2] row_mask:0xf bank_mask:0xf
	v_cndmask_b32_e64 v27, v26, v28, s[10:11]
	v_cndmask_b32_e64 v29, v28, v26, s[10:11]
	s_waitcnt lgkmcnt(0)
	v_pk_mul_f32 v[2:3], v[2:3], v[36:37]
	v_pk_mul_f32 v[4:5], v[4:5], v[38:39]
	v_add_f32_dpp v27, v29, v27 quad_perm:[2,3,0,1] row_mask:0xf bank_mask:0xf
	v_pk_mul_f32 v[6:7], v[6:7], v[40:41]
	v_pk_mul_f32 v[8:9], v[8:9], v[42:43]
	v_add_f32_dpp v27, v27, v27 row_shl:4 row_mask:0xf bank_mask:0xf
	ds_write_b32 v33, v27 offset:3584
	s_add_i32 s0, s0, 1
	s_waitcnt lgkmcnt(0)
	s_barrier
	s_cmp_eq_u32 s0, 64
	s_cbranch_scc0 .Lscan_chunk
	s_branch .LBB0_496
